# attention: bias/mask path of the last four tiles branch-free with batched LUT reads; q-block prologue waits only for Q rows (counted vmcnt)
# baseline (speedup 1.0000x reference)
; __device__ __forceinline__ int opaque_tid() { int t = threadIdx.x; asm volatile("" : "+v"(t)); return t; }
; #define ALDS __attribute__((address_space(3)))
; __device__ __forceinline__ float bf2f(short s) { return __uint_as_float(((unsigned)(unsigned short)s) << 16); }
; __device__ __forceinline__ void attn_unit(int b, int h, int qb, const bf16_t* Q, const bf16_t* K, const bf16_t* V, bf16_t* O, ALDS unsigned char* lds,
;                                           float bmax, float lut31, float lam, float kmaxn, const float* subg, float outscale) {
;     const int tid = opaque_tid(), lane = tid & 63, r32 = lane & 31, hi = lane >> 5;
;     const int wid = __builtin_amdgcn_readfirstlane(tid >> 6), comp = wid >> 2, qw = wid & 3;
;     const long rowbase = (long)b * SEQ; const int q0 = qb * QU;
;     const unsigned lds0 = (unsigned)(uintptr_t)lds;
;     ALDS float* lut = (ALDS float*)(lds + L_LUT);
;     const bf16_t* Kh = K + rowbase * DM + h * 128; const bf16_t* Vh = V + rowbase * DM + h * 128;
;     const int gdma = ((lane >> 4) << 2) | (wid & 3);
;     const unsigned dof0 = (unsigned)((4 * wid + (lane >> 4)) * DM + ((lane & 15) ^ gdma) * 8) * 2u, dof1 = dof0 + 32u * DM * 2u;
;     const unsigned kdst = lds0 + L_K + wid * 1024, vdst = lds0 + L_V + wid * 1024;
;     ...
;     const int NT = 2 * (qb + 1);
;     ATT_DMA(0, 0); ATT_DMA(1, 1); if (NT > 2) ATT_DMA(2, 2);
;     const bf16_t* Qw = Q + (rowbase + q0 + qw * 32 + r32) * DM + h * 128 + comp * 64 + hi * 8;
;     bf16x8 qr[4];
; #pragma unroll
;     for (int d0 = 0; d0 < 4; ++d0) qr[d0] = *(const bf16x8*)(Qw + d0 * 16);
;     float ssq = 0.f;
; #pragma unroll
;     for (int d0 = 0; d0 < 4; ++d0)
; #pragma unroll
;         for (int i = 0; i < 8; ++i) { const float f = bf2f(qr[d0][i]); ssq += f * f; }
;     ssq = xadd<32>(ssq);
;     const float bound = sqrtf(ssq) * kmaxn + bmax;
;     const bool needshift = __any(bound > 60.0f);
.LBB0_61:
	s_nop 0
	v_mov_b32_e32 v0, s91
	ds_read_b64 v[0:1], v0
	s_lshl_b32 s0, s82, 2
	s_and_b32 s0, s0, 24
	s_or_b32 s0, s0, s81
	s_and_b32 s1, s82, 1
	s_xor_b32 s6, s0, 63
	s_waitcnt lgkmcnt(0)
	v_readfirstlane_b32 s65, v1
	v_mov_b32_e32 v1, v216
	s_cmp_eq_u32 s1, 0
	s_cselect_b32 s8, s0, s6
	v_readfirstlane_b32 s9, v1
	s_ashr_i32 s83, s9, 6
	v_bfe_u32 v182, v1, 4, 2
	v_readfirstlane_b32 s64, v0
	s_and_b32 s84, s83, 3
	v_lshlrev_b32_e32 v0, 2, v182
	v_lshlrev_b32_e32 v2, 11, v182
	v_and_b32_e32 v183, 15, v1
	v_lshl_or_b32 v2, s83, 13, v2
	v_bitop3_b32 v0, v0, v183, s84 bitop3:0x36
	s_lshl_b32 s63, s83, 10
	v_lshl_or_b32 v192, v0, 4, v2
	s_add_i32 s63, s63, 0
	v_and_b32_e32 v184, 31, v1
	s_lshl_b32 s93, s8, 7
	s_lshl_b32 s86, s84, 5
	s_or_b32 s62, s42, s93
	v_or_b32_e32 v0, s86, v184
	s_ashr_i32 s85, s9, 8
	v_or_b32_e32 v2, s62, v0
	v_mov_b32_e32 v3, s43
	v_and_b32_e32 v186, 63, v1
	v_lshlrev_b64 v[2:3], 11, v[2:3]
	s_lshl_b32 s0, s85, 6
	v_lshrrev_b32_e32 v185, 5, v186
	v_lshl_add_u64 v[2:3], s[56:57], 0, v[2:3]
	s_ashr_i32 s1, s0, 31
	v_lshl_add_u64 v[2:3], s[0:1], 1, v[2:3]
	v_lshlrev_b32_e32 v176, 4, v185
	v_lshl_add_u64 v[2:3], v[2:3], 0, v[176:177]
	global_load_dwordx4 v[140:143], v[2:3], off
	global_load_dwordx4 v[136:139], v[2:3], off offset:32
	global_load_dwordx4 v[132:135], v[2:3], off offset:64
	global_load_dwordx4 v[128:131], v[2:3], off offset:96
	s_mov_b32 s0, m0
	s_mov_b32 m0, s63
	s_nop 0
	global_load_lds_dwordx4 v192, s[44:45]
	s_mov_b32 m0, s0
	v_add_u32_e32 v193, 0x10000, v192
	s_add_i32 s0, s63, 0x2000
	s_mov_b32 s1, m0
	s_mov_b32 m0, s0
	s_nop 0
	global_load_lds_dwordx4 v193, s[44:45]
	s_mov_b32 m0, s1
	s_add_i32 s87, s63, 0x10000
	s_mov_b32 s0, m0
	s_mov_b32 m0, s87
	s_nop 0
	global_load_lds_dwordx4 v192, s[46:47]
	s_mov_b32 m0, s0
	s_add_i32 s0, s63, 0x12000
	s_mov_b32 s1, m0
	s_mov_b32 m0, s0
	s_nop 0
	global_load_lds_dwordx4 v193, s[46:47]
	s_mov_b32 m0, s1
	s_add_i32 s0, s63, 0x4000
	s_mov_b32 s1, m0
	s_mov_b32 m0, s0
	s_nop 0
	global_load_lds_dwordx4 v192, s[48:49]
	s_mov_b32 m0, s1
	s_add_i32 s0, s63, 0x6000
	s_mov_b32 s1, m0
	s_mov_b32 m0, s0
	s_nop 0
	global_load_lds_dwordx4 v193, s[48:49]
	s_mov_b32 m0, s1
	s_add_i32 s0, s63, 0x14000
	s_mov_b32 s1, m0
	s_mov_b32 m0, s0
	s_nop 0
	global_load_lds_dwordx4 v192, s[50:51]
	s_mov_b32 m0, s1
	s_add_i32 s0, s63, 0x16000
	s_mov_b32 s1, m0
	s_mov_b32 m0, s0
	s_nop 0
	global_load_lds_dwordx4 v193, s[50:51]
	s_mov_b32 m0, s1
	s_cmp_lg_u32 s8, 0
	s_cselect_b64 s[6:7], -1, 0
	s_cmp_eq_u32 s8, 0
	s_cbranch_scc1 .LBB0_63
	s_add_i32 s0, s63, 0x8000
	s_mov_b32 s1, m0
	s_mov_b32 m0, s0
	s_nop 0
	global_load_lds_dwordx4 v192, s[52:53]
	s_mov_b32 m0, s1
	s_add_i32 s0, s63, 0xa000
	s_mov_b32 s1, m0
	s_mov_b32 m0, s0
	s_nop 0
	global_load_lds_dwordx4 v193, s[52:53]
	s_mov_b32 m0, s1
	s_add_i32 s0, s63, 0x18000
	s_mov_b32 s1, m0
	s_mov_b32 m0, s0
	s_nop 0
	global_load_lds_dwordx4 v192, s[54:55]
	s_mov_b32 m0, s1
	s_add_i32 s0, s63, 0x1a000
	s_mov_b32 s1, m0
	s_mov_b32 m0, s0
	s_nop 0
	global_load_lds_dwordx4 v193, s[54:55]
	s_mov_b32 m0, s1
.LBB0_63:
	s_andn2_b64 vcc, exec, s[6:7]
	s_waitcnt vmcnt(8) lgkmcnt(0)
	v_and_b32_e32 v6, 0xffff0000, v140
	v_lshlrev_b32_e32 v0, 16, v140
	v_mul_f32_e32 v6, v6, v6
	v_lshlrev_b32_e32 v7, 16, v141
	v_fmac_f32_e32 v6, v0, v0
	v_and_b32_e32 v8, 0xffff0000, v141
	v_fmac_f32_e32 v6, v7, v7
	v_lshlrev_b32_e32 v9, 16, v142
	v_fmac_f32_e32 v6, v8, v8
	v_and_b32_e32 v10, 0xffff0000, v142
	v_fmac_f32_e32 v6, v9, v9
	v_lshlrev_b32_e32 v11, 16, v143
	v_fmac_f32_e32 v6, v10, v10
	v_and_b32_e32 v12, 0xffff0000, v143
	v_fmac_f32_e32 v6, v11, v11
	v_lshlrev_b32_e32 v13, 16, v136
	v_fmac_f32_e32 v6, v12, v12
	v_and_b32_e32 v14, 0xffff0000, v136
	v_fmac_f32_e32 v6, v13, v13
	v_lshlrev_b32_e32 v15, 16, v137
	v_fmac_f32_e32 v6, v14, v14
	v_and_b32_e32 v16, 0xffff0000, v137
	v_fmac_f32_e32 v6, v15, v15
	v_lshlrev_b32_e32 v17, 16, v138
	v_fmac_f32_e32 v6, v16, v16
	v_and_b32_e32 v18, 0xffff0000, v138
	v_fmac_f32_e32 v6, v17, v17
	v_lshlrev_b32_e32 v19, 16, v139
	v_fmac_f32_e32 v6, v18, v18
	v_and_b32_e32 v20, 0xffff0000, v139
	v_fmac_f32_e32 v6, v19, v19
	v_lshlrev_b32_e32 v21, 16, v132
	v_fmac_f32_e32 v6, v20, v20
	v_and_b32_e32 v22, 0xffff0000, v132
	v_fmac_f32_e32 v6, v21, v21
	v_lshlrev_b32_e32 v23, 16, v133
	v_fmac_f32_e32 v6, v22, v22
	v_and_b32_e32 v24, 0xffff0000, v133
	v_fmac_f32_e32 v6, v23, v23
	v_lshlrev_b32_e32 v25, 16, v134
	v_fmac_f32_e32 v6, v24, v24
	v_and_b32_e32 v26, 0xffff0000, v134
	v_fmac_f32_e32 v6, v25, v25
	v_lshlrev_b32_e32 v27, 16, v135
	v_fmac_f32_e32 v6, v26, v26
	v_and_b32_e32 v28, 0xffff0000, v135
	v_fmac_f32_e32 v6, v27, v27
	v_lshlrev_b32_e32 v29, 16, v128
	v_fmac_f32_e32 v6, v28, v28
	v_and_b32_e32 v30, 0xffff0000, v128
	v_fmac_f32_e32 v6, v29, v29
	v_lshlrev_b32_e32 v31, 16, v129
	v_fmac_f32_e32 v6, v30, v30
	v_and_b32_e32 v32, 0xffff0000, v129
	v_and_b32_e32 v3, 0xffff0000, v130
	v_lshlrev_b32_e32 v2, 16, v130
	v_fmac_f32_e32 v6, v31, v31
	v_pk_mul_f32 v[2:3], v[2:3], v[2:3]
	v_fmac_f32_e32 v6, v32, v32
	v_and_b32_e32 v5, 0xffff0000, v131
	v_lshlrev_b32_e32 v4, 16, v131
	v_add_f32_e32 v0, v2, v6
	v_pk_mul_f32 v[4:5], v[4:5], v[4:5]
	v_add_f32_e32 v0, v3, v0
	v_add_f32_e32 v0, v4, v0
	v_add_f32_e32 v0, v5, v0
	v_mov_b32_e32 v2, v0
	s_nop 1
	v_permlane32_swap_b32_e32 v0, v2
	v_add_f32_e32 v0, v0, v2
	v_mul_f32_e32 v2, 0x4f800000, v0
	v_cmp_gt_f32_e64 s[0:1], s97, v0
	s_nop 1
	v_cndmask_b32_e64 v0, v0, v2, s[0:1]
	v_sqrt_f32_e32 v2, v0
	s_nop 0
	v_add_u32_e32 v3, -1, v2
	v_add_u32_e32 v4, 1, v2
	v_fma_f32 v5, -v3, v2, v0
	v_fma_f32 v6, -v4, v2, v0
	v_cmp_ge_f32_e64 s[6:7], 0, v5
	s_nop 1
	v_cndmask_b32_e64 v2, v2, v3, s[6:7]
	v_cmp_lt_f32_e64 s[6:7], 0, v6
	s_nop 1
	v_cndmask_b32_e64 v2, v2, v4, s[6:7]
	v_mul_f32_e32 v3, 0x37800000, v2
	v_cndmask_b32_e64 v2, v2, v3, s[0:1]
	v_cmp_class_f32_e64 s[0:1], v0, v221
	s_nop 1
	v_cndmask_b32_e64 v0, v2, v0, s[0:1]
	v_fma_f32 v0, v180, v0, v181
	s_mov_b32 s0, 0x42700000
	v_cmp_lt_f32_e64 s[0:1], s0, v0
	s_cbranch_vccnz .LBB0_232
	s_waitcnt vmcnt(8) lgkmcnt(0)
	s_barrier
	s_cbranch_execnz .LBB0_66

.Lattn_b_nodma3:
	ds_read_b128 v[144:147], v115 offset:8192
	s_waitcnt lgkmcnt(4)
	v_mfma_f32_32x32x16_bf16 v[34:49], v[80:83], v[238:241], v[34:49]
	s_waitcnt lgkmcnt(2)
	v_mfma_f32_32x32x16_bf16 v[50:65], v[80:83], v[242:245], v[50:65]
	s_add_i32 s0, s0, -2
	s_cmp_lt_i32 s0, s70
	s_waitcnt lgkmcnt(0)
	v_mfma_f32_32x32x16_bf16 v[96:111], v[172:175], v[140:143], 0
	v_mfma_f32_32x32x16_bf16 v[80:95], v[168:171], v[140:143], 0
	v_mfma_f32_32x32x16_bf16 v[96:111], v[164:167], v[136:139], v[96:111]
	v_mfma_f32_32x32x16_bf16 v[80:95], v[160:163], v[136:139], v[80:95]
	v_mfma_f32_32x32x16_bf16 v[96:111], v[156:159], v[132:135], v[96:111]
	v_mfma_f32_32x32x16_bf16 v[80:95], v[152:155], v[132:135], v[80:95]
	v_mfma_f32_32x32x16_bf16 v[96:111], v[148:151], v[128:131], v[96:111]
	s_nop 1
	v_mfma_f32_32x32x16_bf16 v[80:95], v[144:147], v[128:131], v[80:95]
	s_cbranch_scc1 .LBB0_142
	s_mov_b32 s100, 0x20000
	v_add_u32_e32 v112, 27, v209
	v_min_u32_e32 v112, 0x7f, v112
	v_lshl_add_u32 v112, v112, 2, s100
	ds_read_b32 v112, v112
	v_add_u32_e32 v113, 26, v209
	v_min_u32_e32 v113, 0x7f, v113
	v_lshl_add_u32 v113, v113, 2, s100
	ds_read_b32 v113, v113
	v_add_u32_e32 v114, 25, v209
	v_min_u32_e32 v114, 0x7f, v114
	v_lshl_add_u32 v114, v114, 2, s100
	ds_read_b32 v114, v114
	v_add_u32_e32 v115, 24, v209
	v_min_u32_e32 v115, 0x7f, v115
	v_lshl_add_u32 v115, v115, 2, s100
	ds_read_b32 v115, v115
	v_add_u32_e32 v116, 19, v209
	v_min_u32_e32 v116, 0x7f, v116
	v_lshl_add_u32 v116, v116, 2, s100
	ds_read_b32 v116, v116
	v_add_u32_e32 v117, 18, v209
	v_min_u32_e32 v117, 0x7f, v117
	v_lshl_add_u32 v117, v117, 2, s100
	ds_read_b32 v117, v117
	v_add_u32_e32 v118, 17, v209
	v_min_u32_e32 v118, 0x7f, v118
	v_lshl_add_u32 v118, v118, 2, s100
	ds_read_b32 v118, v118
	v_add_u32_e32 v119, 16, v209
	v_min_u32_e32 v119, 0x7f, v119
	v_lshl_add_u32 v119, v119, 2, s100
	ds_read_b32 v119, v119
	v_add_u32_e32 v120, 11, v209
	v_min_u32_e32 v120, 0x7f, v120
	v_lshl_add_u32 v120, v120, 2, s100
	ds_read_b32 v120, v120
	v_add_u32_e32 v121, 10, v209
	v_min_u32_e32 v121, 0x7f, v121
	v_lshl_add_u32 v121, v121, 2, s100
	ds_read_b32 v121, v121
	v_add_u32_e32 v122, 9, v209
	v_min_u32_e32 v122, 0x7f, v122
	v_lshl_add_u32 v122, v122, 2, s100
	ds_read_b32 v122, v122
	v_add_u32_e32 v123, 8, v209
	v_min_u32_e32 v123, 0x7f, v123
	v_lshl_add_u32 v123, v123, 2, s100
	ds_read_b32 v123, v123
	v_add_u32_e32 v124, 3, v209
	v_min_u32_e32 v124, 0x7f, v124
	v_lshl_add_u32 v124, v124, 2, s100
	ds_read_b32 v124, v124
	v_add_u32_e32 v125, 2, v209
	v_min_u32_e32 v125, 0x7f, v125
	v_lshl_add_u32 v125, v125, 2, s100
	ds_read_b32 v125, v125
	v_add_u32_e32 v126, 1, v209
	v_min_u32_e32 v126, 0x7f, v126
	v_lshl_add_u32 v126, v126, 2, s100
	ds_read_b32 v126, v126
	v_min_u32_e32 v127, 0x7f, v209
	v_lshl_add_u32 v127, v127, 2, s100
	ds_read_b32 v127, v127
	v_cmp_gt_i32_e32 vcc, -27, v209
	s_waitcnt lgkmcnt(15)
	v_add_f32_e32 v96, v96, v112
	v_cndmask_b32_e32 v96, v96, v225, vcc
	v_add_u32_e32 v112, -5, v209
	v_min_u32_e32 v112, 0x7f, v112
	v_lshl_add_u32 v112, v112, 2, s100
	ds_read_b32 v112, v112
	v_cmp_gt_i32_e32 vcc, -26, v209
	s_waitcnt lgkmcnt(15)
	v_add_f32_e32 v97, v97, v113
	v_cndmask_b32_e32 v97, v97, v225, vcc
	v_add_u32_e32 v113, -6, v209
	v_min_u32_e32 v113, 0x7f, v113
	v_lshl_add_u32 v113, v113, 2, s100
	ds_read_b32 v113, v113
	v_cmp_gt_i32_e32 vcc, -25, v209
	s_waitcnt lgkmcnt(15)
	v_add_f32_e32 v98, v98, v114
	v_cndmask_b32_e32 v98, v98, v225, vcc
	v_add_u32_e32 v114, -7, v209
	v_min_u32_e32 v114, 0x7f, v114
	v_lshl_add_u32 v114, v114, 2, s100
	ds_read_b32 v114, v114
	v_cmp_gt_i32_e32 vcc, -24, v209
	s_waitcnt lgkmcnt(15)
	v_add_f32_e32 v99, v99, v115
	v_cndmask_b32_e32 v99, v99, v225, vcc
	v_add_u32_e32 v115, -8, v209
	v_min_u32_e32 v115, 0x7f, v115
	v_lshl_add_u32 v115, v115, 2, s100
	ds_read_b32 v115, v115
	v_cmp_gt_i32_e32 vcc, -19, v209
	s_waitcnt lgkmcnt(15)
	v_add_f32_e32 v100, v100, v116
	v_cndmask_b32_e32 v100, v100, v225, vcc
	v_add_u32_e32 v116, -13, v209
	v_min_u32_e32 v116, 0x7f, v116
	v_lshl_add_u32 v116, v116, 2, s100
	ds_read_b32 v116, v116
	v_cmp_gt_i32_e32 vcc, -18, v209
	s_waitcnt lgkmcnt(15)
	v_add_f32_e32 v101, v101, v117
	v_cndmask_b32_e32 v101, v101, v225, vcc
	v_add_u32_e32 v117, -14, v209
	v_min_u32_e32 v117, 0x7f, v117
	v_lshl_add_u32 v117, v117, 2, s100
	ds_read_b32 v117, v117
	v_cmp_gt_i32_e32 vcc, -17, v209
	s_waitcnt lgkmcnt(15)
	v_add_f32_e32 v102, v102, v118
	v_cndmask_b32_e32 v102, v102, v225, vcc
	v_add_u32_e32 v118, -15, v209
	v_min_u32_e32 v118, 0x7f, v118
	v_lshl_add_u32 v118, v118, 2, s100
	ds_read_b32 v118, v118
	v_cmp_gt_i32_e32 vcc, -16, v209
	s_waitcnt lgkmcnt(15)
	v_add_f32_e32 v103, v103, v119
	v_cndmask_b32_e32 v103, v103, v225, vcc
	v_add_u32_e32 v119, -16, v209
	v_min_u32_e32 v119, 0x7f, v119
	v_lshl_add_u32 v119, v119, 2, s100
	ds_read_b32 v119, v119
	v_cmp_gt_i32_e32 vcc, -11, v209
	s_waitcnt lgkmcnt(15)
	v_add_f32_e32 v104, v104, v120
	v_cndmask_b32_e32 v104, v104, v225, vcc
	v_add_u32_e32 v120, -21, v209
	v_min_u32_e32 v120, 0x7f, v120
	v_lshl_add_u32 v120, v120, 2, s100
	ds_read_b32 v120, v120
	v_cmp_gt_i32_e32 vcc, -10, v209
	s_waitcnt lgkmcnt(15)
	v_add_f32_e32 v105, v105, v121
	v_cndmask_b32_e32 v105, v105, v225, vcc
	v_add_u32_e32 v121, -22, v209
	v_min_u32_e32 v121, 0x7f, v121
	v_lshl_add_u32 v121, v121, 2, s100
	ds_read_b32 v121, v121
	v_cmp_gt_i32_e32 vcc, -9, v209
	s_waitcnt lgkmcnt(15)
	v_add_f32_e32 v106, v106, v122
	v_cndmask_b32_e32 v106, v106, v225, vcc
	v_add_u32_e32 v122, -23, v209
	v_min_u32_e32 v122, 0x7f, v122
	v_lshl_add_u32 v122, v122, 2, s100
	ds_read_b32 v122, v122
	v_cmp_gt_i32_e32 vcc, -8, v209
	s_waitcnt lgkmcnt(15)
	v_add_f32_e32 v107, v107, v123
	v_cndmask_b32_e32 v107, v107, v225, vcc
	v_add_u32_e32 v123, -24, v209
	v_min_u32_e32 v123, 0x7f, v123
	v_lshl_add_u32 v123, v123, 2, s100
	ds_read_b32 v123, v123
	v_cmp_gt_i32_e32 vcc, -3, v209
	s_waitcnt lgkmcnt(15)
	v_add_f32_e32 v108, v108, v124
	v_cndmask_b32_e32 v108, v108, v225, vcc
	v_add_u32_e32 v124, -29, v209
	v_min_u32_e32 v124, 0x7f, v124
	v_lshl_add_u32 v124, v124, 2, s100
	ds_read_b32 v124, v124
	v_cmp_gt_i32_e32 vcc, -2, v209
	s_waitcnt lgkmcnt(15)
	v_add_f32_e32 v109, v109, v125
	v_cndmask_b32_e32 v109, v109, v225, vcc
	v_add_u32_e32 v125, -30, v209
	v_min_u32_e32 v125, 0x7f, v125
	v_lshl_add_u32 v125, v125, 2, s100
	ds_read_b32 v125, v125
	v_cmp_gt_i32_e32 vcc, -1, v209
	s_waitcnt lgkmcnt(15)
	v_add_f32_e32 v110, v110, v126
	v_cndmask_b32_e32 v110, v110, v225, vcc
	v_add_u32_e32 v126, -31, v209
	v_min_u32_e32 v126, 0x7f, v126
	v_lshl_add_u32 v126, v126, 2, s100
	ds_read_b32 v126, v126
	v_cmp_gt_i32_e32 vcc, 0, v209
	s_waitcnt lgkmcnt(15)
	v_add_f32_e32 v111, v111, v127
	v_cndmask_b32_e32 v111, v111, v225, vcc
	v_add_u32_e32 v127, -32, v209
	v_min_u32_e32 v127, 0x7f, v127
	v_lshl_add_u32 v127, v127, 2, s100
	ds_read_b32 v127, v127
	v_cmp_gt_i32_e32 vcc, 5, v209
	s_waitcnt lgkmcnt(15)
	v_add_f32_e32 v80, v80, v112
	v_cndmask_b32_e32 v80, v80, v225, vcc
	v_cmp_gt_i32_e32 vcc, 6, v209
	s_waitcnt lgkmcnt(14)
	v_add_f32_e32 v81, v81, v113
	v_cndmask_b32_e32 v81, v81, v225, vcc
	v_cmp_gt_i32_e32 vcc, 7, v209
	s_waitcnt lgkmcnt(13)
	v_add_f32_e32 v82, v82, v114
	v_cndmask_b32_e32 v82, v82, v225, vcc
	v_cmp_gt_i32_e32 vcc, 8, v209
	s_waitcnt lgkmcnt(12)
	v_add_f32_e32 v83, v83, v115
	v_cndmask_b32_e32 v83, v83, v225, vcc
	v_cmp_gt_i32_e32 vcc, 13, v209
	s_waitcnt lgkmcnt(11)
	v_add_f32_e32 v84, v84, v116
	v_cndmask_b32_e32 v84, v84, v225, vcc
	v_cmp_gt_i32_e32 vcc, 14, v209
	s_waitcnt lgkmcnt(10)
	v_add_f32_e32 v85, v85, v117
	v_cndmask_b32_e32 v85, v85, v225, vcc
	v_cmp_gt_i32_e32 vcc, 15, v209
	s_waitcnt lgkmcnt(9)
	v_add_f32_e32 v86, v86, v118
	v_cndmask_b32_e32 v86, v86, v225, vcc
	v_cmp_gt_i32_e32 vcc, 16, v209
	s_waitcnt lgkmcnt(8)
	v_add_f32_e32 v87, v87, v119
	v_cndmask_b32_e32 v87, v87, v225, vcc
	v_cmp_gt_i32_e32 vcc, 21, v209
	s_waitcnt lgkmcnt(7)
	v_add_f32_e32 v88, v88, v120
	v_cndmask_b32_e32 v88, v88, v225, vcc
	v_cmp_gt_i32_e32 vcc, 22, v209
	s_waitcnt lgkmcnt(6)
	v_add_f32_e32 v89, v89, v121
	v_cndmask_b32_e32 v89, v89, v225, vcc
	v_cmp_gt_i32_e32 vcc, 23, v209
	s_waitcnt lgkmcnt(5)
	v_add_f32_e32 v90, v90, v122
	v_cndmask_b32_e32 v90, v90, v225, vcc
	v_cmp_gt_i32_e32 vcc, 24, v209
	s_waitcnt lgkmcnt(4)
	v_add_f32_e32 v91, v91, v123
	v_cndmask_b32_e32 v91, v91, v225, vcc
	v_cmp_gt_i32_e32 vcc, 29, v209
	s_waitcnt lgkmcnt(3)
	v_add_f32_e32 v92, v92, v124
	v_cndmask_b32_e32 v92, v92, v225, vcc
	v_cmp_gt_i32_e32 vcc, 30, v209
	s_waitcnt lgkmcnt(2)
	v_add_f32_e32 v93, v93, v125
	v_cndmask_b32_e32 v93, v93, v225, vcc
	v_cmp_gt_i32_e32 vcc, 31, v209
	s_waitcnt lgkmcnt(1)
	v_add_f32_e32 v94, v94, v126
	v_cndmask_b32_e32 v94, v94, v225, vcc
	v_cmp_gt_i32_e32 vcc, 32, v209
	s_waitcnt lgkmcnt(0)
	v_add_f32_e32 v95, v95, v127
	v_cndmask_b32_e32 v95, v95, v225, vcc

.LBB0_154:
.LBB0_155:
	s_add_i32 s0, s93, 0xffff8000
	s_and_b32 s0, s0, 0xc000
	v_add_u32_e32 v112, s0, v198
	v_add_u32_e32 v113, v112, v194
	ds_read_b128 v[172:175], v113
	ds_read_b128 v[168:171], v113 offset:8192
	v_add_u32_e32 v113, v112, v195
	ds_read_b128 v[164:167], v113
	ds_read_b128 v[160:163], v113 offset:8192
	v_add_u32_e32 v113, v112, v196
	v_add_u32_e32 v112, v112, v197
	ds_read_b128 v[156:159], v113
	ds_read_b128 v[152:155], v113 offset:8192
	ds_read_b128 v[148:151], v112
	ds_read_b128 v[144:147], v112 offset:8192
	s_cmp_lt_i32 s70, s99
	s_cbranch_scc1 .LBB0_189
	s_mov_b32 s100, 0x20000
	v_add_u32_e32 v112, 27, v203
	v_min_u32_e32 v112, 0x7f, v112
	v_lshl_add_u32 v112, v112, 2, s100
	ds_read_b32 v112, v112
	v_add_u32_e32 v113, 26, v203
	v_min_u32_e32 v113, 0x7f, v113
	v_lshl_add_u32 v113, v113, 2, s100
	ds_read_b32 v113, v113
	v_add_u32_e32 v114, 25, v203
	v_min_u32_e32 v114, 0x7f, v114
	v_lshl_add_u32 v114, v114, 2, s100
	ds_read_b32 v114, v114
	v_add_u32_e32 v115, 24, v203
	v_min_u32_e32 v115, 0x7f, v115
	v_lshl_add_u32 v115, v115, 2, s100
	ds_read_b32 v115, v115
	v_add_u32_e32 v116, 19, v203
	v_min_u32_e32 v116, 0x7f, v116
	v_lshl_add_u32 v116, v116, 2, s100
	ds_read_b32 v116, v116
	v_add_u32_e32 v117, 18, v203
	v_min_u32_e32 v117, 0x7f, v117
	v_lshl_add_u32 v117, v117, 2, s100
	ds_read_b32 v117, v117
	v_add_u32_e32 v118, 17, v203
	v_min_u32_e32 v118, 0x7f, v118
	v_lshl_add_u32 v118, v118, 2, s100
	ds_read_b32 v118, v118
	v_add_u32_e32 v119, 16, v203
	v_min_u32_e32 v119, 0x7f, v119
	v_lshl_add_u32 v119, v119, 2, s100
	ds_read_b32 v119, v119
	v_add_u32_e32 v120, 11, v203
	v_min_u32_e32 v120, 0x7f, v120
	v_lshl_add_u32 v120, v120, 2, s100
	ds_read_b32 v120, v120
	v_add_u32_e32 v121, 10, v203
	v_min_u32_e32 v121, 0x7f, v121
	v_lshl_add_u32 v121, v121, 2, s100
	ds_read_b32 v121, v121
	v_add_u32_e32 v122, 9, v203
	v_min_u32_e32 v122, 0x7f, v122
	v_lshl_add_u32 v122, v122, 2, s100
	ds_read_b32 v122, v122
	v_add_u32_e32 v123, 8, v203
	v_min_u32_e32 v123, 0x7f, v123
	v_lshl_add_u32 v123, v123, 2, s100
	ds_read_b32 v123, v123
	v_add_u32_e32 v124, 3, v203
	v_min_u32_e32 v124, 0x7f, v124
	v_lshl_add_u32 v124, v124, 2, s100
	ds_read_b32 v124, v124
	v_add_u32_e32 v125, 2, v203
	v_min_u32_e32 v125, 0x7f, v125
	v_lshl_add_u32 v125, v125, 2, s100
	ds_read_b32 v125, v125
	v_add_u32_e32 v126, 1, v203
	v_min_u32_e32 v126, 0x7f, v126
	v_lshl_add_u32 v126, v126, 2, s100
	ds_read_b32 v126, v126
	v_min_u32_e32 v127, 0x7f, v203
	v_lshl_add_u32 v127, v127, 2, s100
	ds_read_b32 v127, v127
	v_cmp_gt_i32_e32 vcc, -27, v203
	s_waitcnt lgkmcnt(15)
	v_add_f32_e32 v96, v96, v112
	v_cndmask_b32_e32 v96, v96, v225, vcc
	v_add_u32_e32 v112, -5, v203
	v_min_u32_e32 v112, 0x7f, v112
	v_lshl_add_u32 v112, v112, 2, s100
	ds_read_b32 v112, v112
	v_cmp_gt_i32_e32 vcc, -26, v203
	s_waitcnt lgkmcnt(15)
	v_add_f32_e32 v97, v97, v113
	v_cndmask_b32_e32 v97, v97, v225, vcc
	v_add_u32_e32 v113, -6, v203
	v_min_u32_e32 v113, 0x7f, v113
	v_lshl_add_u32 v113, v113, 2, s100
	ds_read_b32 v113, v113
	v_cmp_gt_i32_e32 vcc, -25, v203
	s_waitcnt lgkmcnt(15)
	v_add_f32_e32 v98, v98, v114
	v_cndmask_b32_e32 v98, v98, v225, vcc
	v_add_u32_e32 v114, -7, v203
	v_min_u32_e32 v114, 0x7f, v114
	v_lshl_add_u32 v114, v114, 2, s100
	ds_read_b32 v114, v114
	v_cmp_gt_i32_e32 vcc, -24, v203
	s_waitcnt lgkmcnt(15)
	v_add_f32_e32 v99, v99, v115
	v_cndmask_b32_e32 v99, v99, v225, vcc
	v_add_u32_e32 v115, -8, v203
	v_min_u32_e32 v115, 0x7f, v115
	v_lshl_add_u32 v115, v115, 2, s100
	ds_read_b32 v115, v115
	v_cmp_gt_i32_e32 vcc, -19, v203
	s_waitcnt lgkmcnt(15)
	v_add_f32_e32 v100, v100, v116
	v_cndmask_b32_e32 v100, v100, v225, vcc
	v_add_u32_e32 v116, -13, v203
	v_min_u32_e32 v116, 0x7f, v116
	v_lshl_add_u32 v116, v116, 2, s100
	ds_read_b32 v116, v116
	v_cmp_gt_i32_e32 vcc, -18, v203
	s_waitcnt lgkmcnt(15)
	v_add_f32_e32 v101, v101, v117
	v_cndmask_b32_e32 v101, v101, v225, vcc
	v_add_u32_e32 v117, -14, v203
	v_min_u32_e32 v117, 0x7f, v117
	v_lshl_add_u32 v117, v117, 2, s100
	ds_read_b32 v117, v117
	v_cmp_gt_i32_e32 vcc, -17, v203
	s_waitcnt lgkmcnt(15)
	v_add_f32_e32 v102, v102, v118
	v_cndmask_b32_e32 v102, v102, v225, vcc
	v_add_u32_e32 v118, -15, v203
	v_min_u32_e32 v118, 0x7f, v118
	v_lshl_add_u32 v118, v118, 2, s100
	ds_read_b32 v118, v118
	v_cmp_gt_i32_e32 vcc, -16, v203
	s_waitcnt lgkmcnt(15)
	v_add_f32_e32 v103, v103, v119
	v_cndmask_b32_e32 v103, v103, v225, vcc
	v_add_u32_e32 v119, -16, v203
	v_min_u32_e32 v119, 0x7f, v119
	v_lshl_add_u32 v119, v119, 2, s100
	ds_read_b32 v119, v119
	v_cmp_gt_i32_e32 vcc, -11, v203
	s_waitcnt lgkmcnt(15)
	v_add_f32_e32 v104, v104, v120
	v_cndmask_b32_e32 v104, v104, v225, vcc
	v_add_u32_e32 v120, -21, v203
	v_min_u32_e32 v120, 0x7f, v120
	v_lshl_add_u32 v120, v120, 2, s100
	ds_read_b32 v120, v120
	v_cmp_gt_i32_e32 vcc, -10, v203
	s_waitcnt lgkmcnt(15)
	v_add_f32_e32 v105, v105, v121
	v_cndmask_b32_e32 v105, v105, v225, vcc
	v_add_u32_e32 v121, -22, v203
	v_min_u32_e32 v121, 0x7f, v121
	v_lshl_add_u32 v121, v121, 2, s100
	ds_read_b32 v121, v121
	v_cmp_gt_i32_e32 vcc, -9, v203
	s_waitcnt lgkmcnt(15)
	v_add_f32_e32 v106, v106, v122
	v_cndmask_b32_e32 v106, v106, v225, vcc
	v_add_u32_e32 v122, -23, v203
	v_min_u32_e32 v122, 0x7f, v122
	v_lshl_add_u32 v122, v122, 2, s100
	ds_read_b32 v122, v122
	v_cmp_gt_i32_e32 vcc, -8, v203
	s_waitcnt lgkmcnt(15)
	v_add_f32_e32 v107, v107, v123
	v_cndmask_b32_e32 v107, v107, v225, vcc
	v_add_u32_e32 v123, -24, v203
	v_min_u32_e32 v123, 0x7f, v123
	v_lshl_add_u32 v123, v123, 2, s100
	ds_read_b32 v123, v123
	v_cmp_gt_i32_e32 vcc, -3, v203
	s_waitcnt lgkmcnt(15)
	v_add_f32_e32 v108, v108, v124
	v_cndmask_b32_e32 v108, v108, v225, vcc
	v_add_u32_e32 v124, -29, v203
	v_min_u32_e32 v124, 0x7f, v124
	v_lshl_add_u32 v124, v124, 2, s100
	ds_read_b32 v124, v124
	v_cmp_gt_i32_e32 vcc, -2, v203
	s_waitcnt lgkmcnt(15)
	v_add_f32_e32 v109, v109, v125
	v_cndmask_b32_e32 v109, v109, v225, vcc
	v_add_u32_e32 v125, -30, v203
	v_min_u32_e32 v125, 0x7f, v125
	v_lshl_add_u32 v125, v125, 2, s100
	ds_read_b32 v125, v125
	v_cmp_gt_i32_e32 vcc, -1, v203
	s_waitcnt lgkmcnt(15)
	v_add_f32_e32 v110, v110, v126
	v_cndmask_b32_e32 v110, v110, v225, vcc
	v_add_u32_e32 v126, -31, v203
	v_min_u32_e32 v126, 0x7f, v126
	v_lshl_add_u32 v126, v126, 2, s100
	ds_read_b32 v126, v126
	v_cmp_gt_i32_e32 vcc, 0, v203
	s_waitcnt lgkmcnt(15)
	v_add_f32_e32 v111, v111, v127
	v_cndmask_b32_e32 v111, v111, v225, vcc
	v_add_u32_e32 v127, -32, v203
	v_min_u32_e32 v127, 0x7f, v127
	v_lshl_add_u32 v127, v127, 2, s100
	ds_read_b32 v127, v127
	v_cmp_gt_i32_e32 vcc, 5, v203
	s_waitcnt lgkmcnt(15)
	v_add_f32_e32 v80, v80, v112
	v_cndmask_b32_e32 v80, v80, v225, vcc
	v_cmp_gt_i32_e32 vcc, 6, v203
	s_waitcnt lgkmcnt(14)
	v_add_f32_e32 v81, v81, v113
	v_cndmask_b32_e32 v81, v81, v225, vcc
	v_cmp_gt_i32_e32 vcc, 7, v203
	s_waitcnt lgkmcnt(13)
	v_add_f32_e32 v82, v82, v114
	v_cndmask_b32_e32 v82, v82, v225, vcc
	v_cmp_gt_i32_e32 vcc, 8, v203
	s_waitcnt lgkmcnt(12)
	v_add_f32_e32 v83, v83, v115
	v_cndmask_b32_e32 v83, v83, v225, vcc
	v_cmp_gt_i32_e32 vcc, 13, v203
	s_waitcnt lgkmcnt(11)
	v_add_f32_e32 v84, v84, v116
	v_cndmask_b32_e32 v84, v84, v225, vcc
	v_cmp_gt_i32_e32 vcc, 14, v203
	s_waitcnt lgkmcnt(10)
	v_add_f32_e32 v85, v85, v117
	v_cndmask_b32_e32 v85, v85, v225, vcc
	v_cmp_gt_i32_e32 vcc, 15, v203
	s_waitcnt lgkmcnt(9)
	v_add_f32_e32 v86, v86, v118
	v_cndmask_b32_e32 v86, v86, v225, vcc
	v_cmp_gt_i32_e32 vcc, 16, v203
	s_waitcnt lgkmcnt(8)
	v_add_f32_e32 v87, v87, v119
	v_cndmask_b32_e32 v87, v87, v225, vcc
	v_cmp_gt_i32_e32 vcc, 21, v203
	s_waitcnt lgkmcnt(7)
	v_add_f32_e32 v88, v88, v120
	v_cndmask_b32_e32 v88, v88, v225, vcc
	v_cmp_gt_i32_e32 vcc, 22, v203
	s_waitcnt lgkmcnt(6)
	v_add_f32_e32 v89, v89, v121
	v_cndmask_b32_e32 v89, v89, v225, vcc
	v_cmp_gt_i32_e32 vcc, 23, v203
	s_waitcnt lgkmcnt(5)
	v_add_f32_e32 v90, v90, v122
	v_cndmask_b32_e32 v90, v90, v225, vcc
	v_cmp_gt_i32_e32 vcc, 24, v203
	s_waitcnt lgkmcnt(4)
	v_add_f32_e32 v91, v91, v123
	v_cndmask_b32_e32 v91, v91, v225, vcc
	v_cmp_gt_i32_e32 vcc, 29, v203
	s_waitcnt lgkmcnt(3)
	v_add_f32_e32 v92, v92, v124
	v_cndmask_b32_e32 v92, v92, v225, vcc
	v_cmp_gt_i32_e32 vcc, 30, v203
	s_waitcnt lgkmcnt(2)
	v_add_f32_e32 v93, v93, v125
	v_cndmask_b32_e32 v93, v93, v225, vcc
	v_cmp_gt_i32_e32 vcc, 31, v203
	s_waitcnt lgkmcnt(1)
	v_add_f32_e32 v94, v94, v126
	v_cndmask_b32_e32 v94, v94, v225, vcc
	v_cmp_gt_i32_e32 vcc, 32, v203
	s_waitcnt lgkmcnt(0)
	v_add_f32_e32 v95, v95, v127
	v_cndmask_b32_e32 v95, v95, v225, vcc
